# attention loop with threshold 8 plus per-half-wave running row sums (the cross-half sum is done once per item instead of once per tile)
# baseline (speedup 1.0000x reference)
.Latt_cont_a:
	v_exp_f32_e32 v112, v112
	v_exp_f32_e32 v113, v113
	v_exp_f32_e32 v114, v114
	v_exp_f32_e32 v115, v115
	v_exp_f32_e32 v116, v116
	v_exp_f32_e32 v117, v117
	v_exp_f32_e32 v118, v118
	v_exp_f32_e32 v119, v119
	v_add_f32_e32 v183, v112, v113
	v_add_f32_e32 v183, v183, v114
	v_add_f32_e32 v183, v183, v115
	v_add_f32_e32 v183, v183, v116
	v_add_f32_e32 v183, v183, v117
	v_add_f32_e32 v183, v183, v118
	v_add_f32_e32 v183, v183, v119
	v_cvt_pk_bf16_f32 v112, v112, v113
	v_cvt_pk_bf16_f32 v113, v114, v115
	v_cvt_pk_bf16_f32 v114, v116, v117
	v_cvt_pk_bf16_f32 v115, v118, v119
	v_exp_f32_e32 v120, v120
	v_exp_f32_e32 v121, v121
	s_waitcnt lgkmcnt(8)
	v_mfma_f32_32x32x16_bf16 v[48:63], v[232:235], v[112:115], v[48:63]
	v_exp_f32_e32 v122, v122
	v_exp_f32_e32 v123, v123
	v_exp_f32_e32 v124, v124
	v_mfma_f32_32x32x16_bf16 v[32:47], v[236:239], v[112:115], v[32:47]
	v_exp_f32_e32 v125, v125
	v_exp_f32_e32 v126, v126
	v_exp_f32_e32 v127, v127
	v_mfma_f32_32x32x16_bf16 v[16:31], v[240:243], v[112:115], v[16:31]
	v_add_f32_e32 v185, v120, v121
	v_add_f32_e32 v185, v185, v122
	v_add_f32_e32 v185, v185, v123
	v_add_f32_e32 v185, v185, v124
	v_add_f32_e32 v185, v185, v125
	v_add_f32_e32 v185, v185, v126
	v_mfma_f32_32x32x16_bf16 v[0:15], v[244:247], v[112:115], v[0:15]
	ds_read_b128 v[232:235], v167 offset:32768
	ds_read_b128 v[236:239], v167 offset:36864
	ds_read_b128 v[240:243], v167 offset:40960
	ds_read_b128 v[244:247], v167 offset:45056
	v_add_f32_e32 v185, v185, v127
	v_cvt_pk_bf16_f32 v116, v120, v121
	v_cvt_pk_bf16_f32 v117, v122, v123
	v_cvt_pk_bf16_f32 v118, v124, v125
	v_cvt_pk_bf16_f32 v119, v126, v127
	s_nop 0
	s_waitcnt lgkmcnt(8)
	v_mfma_f32_32x32x16_bf16 v[48:63], v[64:67], v[116:119], v[48:63]
	v_exp_f32_e32 v80, v80
	v_exp_f32_e32 v81, v81
	v_exp_f32_e32 v82, v82
	v_mfma_f32_32x32x16_bf16 v[32:47], v[68:71], v[116:119], v[32:47]
	v_exp_f32_e32 v83, v83
	v_exp_f32_e32 v84, v84
	v_exp_f32_e32 v85, v85
	v_mfma_f32_32x32x16_bf16 v[16:31], v[72:75], v[116:119], v[16:31]
	v_exp_f32_e32 v86, v86
	v_exp_f32_e32 v87, v87
	v_add_f32_e32 v187, v80, v81
	v_add_f32_e32 v187, v187, v82
	v_mfma_f32_32x32x16_bf16 v[0:15], v[76:79], v[116:119], v[0:15]
	v_add_f32_e32 v187, v187, v83
	v_add_f32_e32 v187, v187, v84
	v_add_f32_e32 v187, v187, v85
	v_add_f32_e32 v187, v187, v86
	v_add_f32_e32 v187, v187, v87
	v_cvt_pk_bf16_f32 v80, v80, v81
	v_cvt_pk_bf16_f32 v81, v82, v83
	v_cvt_pk_bf16_f32 v82, v84, v85
	v_cvt_pk_bf16_f32 v83, v86, v87
	s_nop 0
	s_waitcnt lgkmcnt(4)
	v_mfma_f32_32x32x16_bf16 v[48:63], v[216:219], v[80:83], v[48:63]
	v_exp_f32_e32 v88, v88
	v_exp_f32_e32 v89, v89
	v_exp_f32_e32 v90, v90
	v_mfma_f32_32x32x16_bf16 v[32:47], v[220:223], v[80:83], v[32:47]
	v_exp_f32_e32 v91, v91
	v_exp_f32_e32 v92, v92
	v_exp_f32_e32 v93, v93
	v_mfma_f32_32x32x16_bf16 v[16:31], v[224:227], v[80:83], v[16:31]
	v_exp_f32_e32 v94, v94
	v_exp_f32_e32 v95, v95
	v_add_f32_e32 v215, v88, v89
	v_add_f32_e32 v215, v215, v90
	v_mfma_f32_32x32x16_bf16 v[0:15], v[228:231], v[80:83], v[0:15]
	v_add_f32_e32 v215, v215, v91
	v_add_f32_e32 v215, v215, v92
	v_add_f32_e32 v215, v215, v93
	v_add_f32_e32 v215, v215, v94
	v_add_f32_e32 v215, v215, v95
	v_cvt_pk_bf16_f32 v84, v88, v89
	v_cvt_pk_bf16_f32 v85, v90, v91
	v_cvt_pk_bf16_f32 v86, v92, v93
	v_cvt_pk_bf16_f32 v87, v94, v95
	s_nop 0
	s_waitcnt lgkmcnt(0)
	v_mfma_f32_32x32x16_bf16 v[48:63], v[232:235], v[84:87], v[48:63]
	v_add_f32_e32 v183, v183, v185
	v_add_f32_e32 v187, v187, v215
	v_add_f32_e32 v183, v183, v187
	v_mfma_f32_32x32x16_bf16 v[32:47], v[236:239], v[84:87], v[32:47]
	v_mfma_f32_32x32x16_bf16 v[16:31], v[240:243], v[84:87], v[16:31]
	v_mfma_f32_32x32x16_bf16 v[0:15], v[244:247], v[84:87], v[0:15]
	v_add_f32_e32 v189, v189, v183
	s_waitcnt vmcnt(0)
	s_barrier
	ds_read_b128 v[64:67], v173 offset:0
	ds_read_b128 v[68:71], v173 offset:4096
	s_add_u32 m0, s44, 0x6000
	ds_read_b128 v[72:75], v171 offset:0
	global_load_lds_dwordx4 v200, s[40:41]
	s_add_u32 m0, s44, 0x6400
	ds_read_b128 v[76:79], v171 offset:4096
	global_load_lds_dwordx4 v190, s[40:41]
	s_add_u32 m0, s45, 0x6000
	ds_read_b128 v[216:219], v169 offset:0
	global_load_lds_dwordx4 v192, s[42:43]
	s_add_u32 m0, s45, 0x6400
	ds_read_b128 v[220:223], v169 offset:4096
	global_load_lds_dwordx4 v194, s[42:43]
	s_add_u32 m0, s45, 0x6800
	ds_read_b128 v[224:227], v167 offset:0
	global_load_lds_dwordx4 v196, s[42:43]
	s_add_u32 m0, s45, 0x6c00
	ds_read_b128 v[228:231], v167 offset:4096
	global_load_lds_dwordx4 v198, s[42:43]
	ds_read_b128 v[232:235], v173 offset:8192
	ds_read_b128 v[236:239], v173 offset:12288
	ds_read_b128 v[240:243], v173 offset:16384
	ds_read_b128 v[244:247], v173 offset:20480
	s_add_u32 s40, s40, 0x18000
	s_addc_u32 s41, s41, 0
	s_add_u32 s42, s42, 0x80
	s_addc_u32 s43, s43, 0
	s_waitcnt lgkmcnt(11)
	v_mfma_f32_32x32x16_bf16 v[112:127], v[64:67], v[140:143], v[96:111]
	ds_read_b128 v[64:67], v171 offset:8192
	s_waitcnt lgkmcnt(11)
	v_mfma_f32_32x32x16_bf16 v[80:95], v[68:71], v[140:143], v[96:111]
	ds_read_b128 v[68:71], v171 offset:12288
	s_waitcnt lgkmcnt(11)
	v_mfma_f32_32x32x16_bf16 v[112:127], v[72:75], v[136:139], v[112:127]
	ds_read_b128 v[72:75], v171 offset:16384
	s_waitcnt lgkmcnt(11)
	v_mfma_f32_32x32x16_bf16 v[80:95], v[76:79], v[136:139], v[80:95]
	ds_read_b128 v[76:79], v171 offset:20480
	s_waitcnt lgkmcnt(11)
	v_mfma_f32_32x32x16_bf16 v[112:127], v[216:219], v[132:135], v[112:127]
	ds_read_b128 v[216:219], v169 offset:8192
	s_waitcnt lgkmcnt(11)
	v_mfma_f32_32x32x16_bf16 v[80:95], v[220:223], v[132:135], v[80:95]
	ds_read_b128 v[220:223], v169 offset:12288
	s_waitcnt lgkmcnt(11)
	v_mfma_f32_32x32x16_bf16 v[112:127], v[224:227], v[128:131], v[112:127]
	ds_read_b128 v[224:227], v169 offset:16384
	s_waitcnt lgkmcnt(11)
	v_mfma_f32_32x32x16_bf16 v[80:95], v[228:231], v[128:131], v[80:95]
	ds_read_b128 v[228:231], v169 offset:20480
	s_nop 7
	s_nop 3
	v_max3_f32 v175, v112, v113, v114
	v_max3_f32 v177, v115, v116, v117
	v_max3_f32 v179, v118, v119, v120
	v_max3_f32 v181, v121, v122, v123
	v_max3_f32 v248, v124, v125, v126
	v_max3_f32 v249, v127, v80, v81
	v_max3_f32 v250, v82, v83, v84
	v_max3_f32 v251, v85, v86, v87
	v_max3_f32 v253, v88, v89, v90
	v_max3_f32 v254, v91, v92, v93
	v_max_f32_e32 v255, v94, v95
	v_max3_f32 v175, v175, v177, v179
	v_max3_f32 v181, v181, v248, v249
	v_max3_f32 v250, v250, v251, v253
	v_max_f32_e32 v254, v254, v255
	v_max3_f32 v175, v175, v181, v250
	v_max_f32_e32 v175, v175, v254
	v_cmp_lt_f32_e32 vcc, 0x41000000, v175
	s_cbranch_vccnz .Latt_resc_b
